# final RMSNorm of prompt rows fused into the down-GEMM epilogue: bf16 x2 tile staged in LDS, per-row sum-of-squares exchanged between the 4 workgroups of a row panel, y written directly (x2 round trip
# baseline (speedup 1.0000x reference)
.Lpeel_p10_exit:
	s_mov_b32 s100, s50
	s_mov_b32 s101, s51
	s_lshr_b32 s98, s8, 3
	v_add_u32_e32 v240, s98, v211
	v_xor_b32_e32 v240, v240, v178
	v_add_u32_e32 v241, s36, v178
	v_lshlrev_b32_e32 v241, 9, v241
	v_lshl_or_b32 v240, v240, 4, v241
	v_add_u32_e32 v241, 0x10000, v240
	v_mov_b32_e32 v146, v178
	v_mov_b32_e32 v152, v211
	s_lshl_b32 s16, s50, 8
	s_add_i32 s16, s16, s36
	v_add_u32_e32 v146, s16, v146
	s_lshl_b32 s16, s51, 8
	s_ashr_i32 s17, s16, 31
	v_lshlrev_b32_e32 v152, 3, v152
	v_ashrrev_i32_e32 v147, 31, v146
	v_ashrrev_i32_e32 v153, 31, v152
	s_or_b64 s[16:17], s[16:17], s[8:9]
	v_lshlrev_b64 v[146:147], 10, v[146:147]
	v_lshl_add_u64 v[152:153], s[16:17], 0, v[152:153]
	v_lshl_add_u64 v[146:147], v[152:153], 0, v[146:147]
	v_lshlrev_b64 v[176:177], 1, v[146:147]
	v_lshl_add_u64 v[146:147], s[10:11], 0, v[176:177]
	global_load_dwordx4 v[152:155], v[146:147], off
	global_load_dwordx4 v[156:159], v[146:147], off offset:256
	v_add_co_u32_e32 v164, vcc, s40, v146
	s_mov_b32 s51, s48
	s_nop 0
	v_addc_co_u32_e32 v165, vcc, 0, v147, vcc
	global_load_dwordx4 v[160:163], v[164:165], off
	s_nop 0
	global_load_dwordx4 v[164:167], v[164:165], off offset:256
	v_add_co_u32_e32 v172, vcc, s35, v146
	s_mov_b32 s50, s49
	s_nop 0
	v_addc_co_u32_e32 v173, vcc, 0, v147, vcc
	global_load_dwordx4 v[168:171], v[172:173], off
	s_nop 0
	global_load_dwordx4 v[172:175], v[172:173], off offset:256
	v_add_co_u32_e32 v184, vcc, s39, v146
	s_mov_b64 s[18:19], s[4:5]
	s_nop 0
	v_addc_co_u32_e32 v185, vcc, 0, v147, vcc
	global_load_dwordx4 v[180:183], v[184:185], off
	s_nop 0
	global_load_dwordx4 v[184:187], v[184:185], off offset:256
	s_mov_b64 s[16:17], s[2:3]
	s_waitcnt vmcnt(0)
	s_cmpk_gt_u32 s26, 0xff
	s_cbranch_scc1 .Lfn_align
	s_barrier
.Lfn_align:
	s_barrier
	v_lshlrev_b32_e32 v188, 16, v152
	v_and_b32_e32 v189, 0xffff0000, v152
	v_lshlrev_b32_e32 v152, 16, v153
	v_and_b32_e32 v153, 0xffff0000, v153
	v_lshlrev_b32_e32 v190, 16, v154
	v_and_b32_e32 v191, 0xffff0000, v154
	v_lshlrev_b32_e32 v154, 16, v155
	v_and_b32_e32 v155, 0xffff0000, v155
	v_pk_add_f32 v[128:129], v[128:129], v[152:153]
	v_pk_add_f32 v[126:127], v[126:127], v[188:189]
	v_pk_add_f32 v[152:153], v[124:125], v[154:155]
	v_pk_add_f32 v[122:123], v[122:123], v[190:191]
	v_lshlrev_b32_e32 v192, 16, v156
	v_and_b32_e32 v193, 0xffff0000, v156
	v_lshlrev_b32_e32 v156, 16, v157
	v_and_b32_e32 v157, 0xffff0000, v157
	v_lshlrev_b32_e32 v194, 16, v158
	v_and_b32_e32 v195, 0xffff0000, v158
	v_lshlrev_b32_e32 v158, 16, v159
	v_and_b32_e32 v159, 0xffff0000, v159
	v_cvt_pk_bf16_f32 v124, v126, v127
	v_cvt_pk_bf16_f32 v125, v128, v129
	v_cvt_pk_bf16_f32 v126, v122, v123
	v_cvt_pk_bf16_f32 v127, v152, v153
	v_lshl_add_u64 v[122:123], s[12:13], 0, v[176:177]
	ds_write_b128 v240, v[124:127] offset:0
	v_pk_add_f32 v[120:121], v[120:121], v[156:157]
	v_pk_add_f32 v[118:119], v[118:119], v[192:193]
	v_pk_add_f32 v[124:125], v[112:113], v[158:159]
	v_pk_add_f32 v[112:113], v[110:111], v[194:195]
	v_lshlrev_b32_e32 v196, 16, v160
	v_and_b32_e32 v197, 0xffff0000, v160
	v_lshlrev_b32_e32 v160, 16, v161
	v_and_b32_e32 v161, 0xffff0000, v161
	v_cvt_pk_bf16_f32 v110, v118, v119
	v_cvt_pk_bf16_f32 v111, v120, v121
	v_cvt_pk_bf16_f32 v112, v112, v113
	v_cvt_pk_bf16_f32 v113, v124, v125
	v_lshlrev_b32_e32 v198, 16, v162
	v_and_b32_e32 v199, 0xffff0000, v162
	v_lshlrev_b32_e32 v162, 16, v163
	v_and_b32_e32 v163, 0xffff0000, v163
	ds_write_b128 v240, v[110:113] offset:256
	v_lshlrev_b32_e32 v200, 16, v164
	v_and_b32_e32 v201, 0xffff0000, v164
	v_pk_add_f32 v[110:111], v[116:117], v[160:161]
	v_pk_add_f32 v[112:113], v[114:115], v[196:197]
	v_pk_add_f32 v[114:115], v[108:109], v[162:163]
	v_pk_add_f32 v[108:109], v[106:107], v[198:199]
	v_cvt_pk_bf16_f32 v107, v110, v111
	v_add_co_u32_e32 v110, vcc, s40, v122
	v_lshlrev_b32_e32 v164, 16, v165
	v_and_b32_e32 v165, 0xffff0000, v165
	v_lshlrev_b32_e32 v202, 16, v166
	v_and_b32_e32 v203, 0xffff0000, v166
	v_lshlrev_b32_e32 v166, 16, v167
	v_and_b32_e32 v167, 0xffff0000, v167
	v_cvt_pk_bf16_f32 v106, v112, v113
	v_cvt_pk_bf16_f32 v108, v108, v109
	v_cvt_pk_bf16_f32 v109, v114, v115
	v_addc_co_u32_e32 v111, vcc, 0, v123, vcc
	ds_write_b128 v240, v[106:109] offset:8448
	v_pk_add_f32 v[104:105], v[104:105], v[164:165]
	v_pk_add_f32 v[102:103], v[102:103], v[200:201]
	v_pk_add_f32 v[106:107], v[96:97], v[166:167]
	v_pk_add_f32 v[96:97], v[94:95], v[202:203]
	v_lshlrev_b32_e32 v206, 16, v168
	v_and_b32_e32 v207, 0xffff0000, v168
	v_lshlrev_b32_e32 v168, 16, v169
	v_and_b32_e32 v169, 0xffff0000, v169
	v_cvt_pk_bf16_f32 v94, v102, v103
	v_cvt_pk_bf16_f32 v95, v104, v105
	v_cvt_pk_bf16_f32 v96, v96, v97
	v_cvt_pk_bf16_f32 v97, v106, v107
	v_lshlrev_b32_e32 v208, 16, v170
	v_and_b32_e32 v209, 0xffff0000, v170
	v_lshlrev_b32_e32 v170, 16, v171
	v_and_b32_e32 v171, 0xffff0000, v171
	ds_write_b128 v240, v[94:97] offset:8192
	v_lshlrev_b32_e32 v212, 16, v172
	v_and_b32_e32 v213, 0xffff0000, v172
	v_pk_add_f32 v[94:95], v[100:101], v[168:169]
	v_pk_add_f32 v[96:97], v[98:99], v[206:207]
	v_pk_add_f32 v[98:99], v[92:93], v[170:171]
	v_pk_add_f32 v[92:93], v[90:91], v[208:209]
	v_cvt_pk_bf16_f32 v91, v94, v95
	v_add_co_u32_e32 v94, vcc, s35, v122
	v_lshlrev_b32_e32 v172, 16, v173
	v_and_b32_e32 v173, 0xffff0000, v173
	v_lshlrev_b32_e32 v214, 16, v174
	v_and_b32_e32 v215, 0xffff0000, v174
	v_lshlrev_b32_e32 v174, 16, v175
	v_and_b32_e32 v175, 0xffff0000, v175
	v_cvt_pk_bf16_f32 v90, v96, v97
	v_cvt_pk_bf16_f32 v92, v92, v93
	v_cvt_pk_bf16_f32 v93, v98, v99
	v_addc_co_u32_e32 v95, vcc, 0, v123, vcc
	ds_write_b128 v240, v[90:93] offset:16384
	v_pk_add_f32 v[88:89], v[88:89], v[172:173]
	v_pk_add_f32 v[86:87], v[86:87], v[212:213]
	v_pk_add_f32 v[90:91], v[80:81], v[174:175]
	v_pk_add_f32 v[80:81], v[78:79], v[214:215]
	v_lshlrev_b32_e32 v216, 16, v180
	v_and_b32_e32 v217, 0xffff0000, v180
	v_lshlrev_b32_e32 v180, 16, v181
	v_and_b32_e32 v181, 0xffff0000, v181
	v_cvt_pk_bf16_f32 v78, v86, v87
	v_cvt_pk_bf16_f32 v79, v88, v89
	v_cvt_pk_bf16_f32 v80, v80, v81
	v_cvt_pk_bf16_f32 v81, v90, v91
	v_lshlrev_b32_e32 v218, 16, v182
	v_and_b32_e32 v219, 0xffff0000, v182
	v_lshlrev_b32_e32 v182, 16, v183
	v_and_b32_e32 v183, 0xffff0000, v183
	ds_write_b128 v240, v[78:81] offset:16640
	v_lshlrev_b32_e32 v220, 16, v184
	v_and_b32_e32 v221, 0xffff0000, v184
	v_pk_add_f32 v[78:79], v[84:85], v[180:181]
	v_pk_add_f32 v[80:81], v[82:83], v[216:217]
	v_pk_add_f32 v[82:83], v[76:77], v[182:183]
	v_pk_add_f32 v[76:77], v[74:75], v[218:219]
	v_cvt_pk_bf16_f32 v75, v78, v79
	v_add_co_u32_e32 v78, vcc, s39, v122
	v_lshlrev_b32_e32 v184, 16, v185
	v_and_b32_e32 v185, 0xffff0000, v185
	v_lshlrev_b32_e32 v222, 16, v186
	v_and_b32_e32 v223, 0xffff0000, v186
	v_lshlrev_b32_e32 v186, 16, v187
	v_and_b32_e32 v187, 0xffff0000, v187
	v_cvt_pk_bf16_f32 v74, v80, v81
	v_cvt_pk_bf16_f32 v76, v76, v77
	v_cvt_pk_bf16_f32 v77, v82, v83
	v_addc_co_u32_e32 v79, vcc, 0, v123, vcc
	ds_write_b128 v240, v[74:77] offset:24832
	v_pk_add_f32 v[72:73], v[72:73], v[184:185]
	v_pk_add_f32 v[70:71], v[70:71], v[220:221]
	v_pk_add_f32 v[74:75], v[68:69], v[186:187]
	v_pk_add_f32 v[68:69], v[66:67], v[222:223]
	v_cvt_pk_bf16_f32 v66, v70, v71
	v_cvt_pk_bf16_f32 v67, v72, v73
	v_cvt_pk_bf16_f32 v68, v68, v69
	v_cvt_pk_bf16_f32 v69, v74, v75
	ds_write_b128 v240, v[66:69] offset:24576
	v_add_co_u32_e32 v70, vcc, s43, v146
	s_nop 1
	v_addc_co_u32_e32 v71, vcc, 0, v147, vcc
	global_load_dwordx4 v[66:69], v[70:71], off
	s_nop 0
	global_load_dwordx4 v[70:73], v[70:71], off offset:256
	v_add_co_u32_e32 v78, vcc, s44, v146
	s_waitcnt vmcnt(0)
	v_lshlrev_b32_e32 v98, 16, v66
	v_addc_co_u32_e32 v79, vcc, 0, v147, vcc
	global_load_dwordx4 v[74:77], v[78:79], off
	s_nop 0
	global_load_dwordx4 v[78:81], v[78:79], off offset:256
	v_add_co_u32_e32 v86, vcc, s45, v146
	v_and_b32_e32 v99, 0xffff0000, v66
	s_nop 0
	v_addc_co_u32_e32 v87, vcc, 0, v147, vcc
	global_load_dwordx4 v[82:85], v[86:87], off
	s_nop 0
	global_load_dwordx4 v[86:89], v[86:87], off offset:256
	v_add_co_u32_e32 v94, vcc, s46, v146
	v_lshlrev_b32_e32 v66, 16, v67
	s_nop 0
	v_addc_co_u32_e32 v95, vcc, 0, v147, vcc
	global_load_dwordx4 v[90:93], v[94:95], off
	s_nop 0
	global_load_dwordx4 v[94:97], v[94:95], off offset:256
	v_and_b32_e32 v67, 0xffff0000, v67
	v_lshlrev_b32_e32 v100, 16, v68
	v_and_b32_e32 v101, 0xffff0000, v68
	v_lshlrev_b32_e32 v68, 16, v69
	v_and_b32_e32 v69, 0xffff0000, v69
	v_pk_add_f32 v[62:63], v[62:63], v[98:99]
	v_pk_add_f32 v[64:65], v[64:65], v[66:67]
	v_pk_add_f32 v[66:67], v[60:61], v[68:69]
	v_pk_add_f32 v[60:61], v[58:59], v[100:101]
	v_cvt_pk_bf16_f32 v58, v62, v63
	v_add_co_u32_e32 v62, vcc, s43, v122
	v_lshlrev_b32_e32 v102, 16, v70
	v_and_b32_e32 v103, 0xffff0000, v70
	v_lshlrev_b32_e32 v70, 16, v71
	v_and_b32_e32 v71, 0xffff0000, v71
	v_lshlrev_b32_e32 v104, 16, v72
	v_and_b32_e32 v105, 0xffff0000, v72
	v_lshlrev_b32_e32 v72, 16, v73
	v_and_b32_e32 v73, 0xffff0000, v73
	v_cvt_pk_bf16_f32 v59, v64, v65
	v_cvt_pk_bf16_f32 v60, v60, v61
	v_cvt_pk_bf16_f32 v61, v66, v67
	v_addc_co_u32_e32 v63, vcc, 0, v123, vcc
	ds_write_b128 v241, v[58:61] offset:0
	v_pk_add_f32 v[56:57], v[56:57], v[70:71]
	v_pk_add_f32 v[54:55], v[54:55], v[102:103]
	v_pk_add_f32 v[58:59], v[48:49], v[72:73]
	v_pk_add_f32 v[48:49], v[46:47], v[104:105]
	v_cvt_pk_bf16_f32 v46, v54, v55
	v_cvt_pk_bf16_f32 v47, v56, v57
	v_cvt_pk_bf16_f32 v48, v48, v49
	v_cvt_pk_bf16_f32 v49, v58, v59
	ds_write_b128 v241, v[46:49] offset:256
	s_waitcnt vmcnt(0)
	v_lshlrev_b32_e32 v106, 16, v74
	v_and_b32_e32 v107, 0xffff0000, v74
	v_lshlrev_b32_e32 v74, 16, v75
	v_and_b32_e32 v75, 0xffff0000, v75
	v_lshlrev_b32_e32 v108, 16, v76
	v_and_b32_e32 v109, 0xffff0000, v76
	v_lshlrev_b32_e32 v76, 16, v77
	v_and_b32_e32 v77, 0xffff0000, v77
	v_pk_add_f32 v[46:47], v[52:53], v[74:75]
	v_pk_add_f32 v[48:49], v[50:51], v[106:107]
	v_pk_add_f32 v[50:51], v[44:45], v[76:77]
	v_pk_add_f32 v[44:45], v[42:43], v[108:109]
	v_cvt_pk_bf16_f32 v43, v46, v47
	v_add_co_u32_e32 v46, vcc, s44, v122
	v_lshlrev_b32_e32 v110, 16, v78
	v_and_b32_e32 v111, 0xffff0000, v78
	v_lshlrev_b32_e32 v78, 16, v79
	v_and_b32_e32 v79, 0xffff0000, v79
	v_lshlrev_b32_e32 v112, 16, v80
	v_and_b32_e32 v113, 0xffff0000, v80
	v_lshlrev_b32_e32 v80, 16, v81
	v_and_b32_e32 v81, 0xffff0000, v81
	v_cvt_pk_bf16_f32 v42, v48, v49
	v_cvt_pk_bf16_f32 v44, v44, v45
	v_cvt_pk_bf16_f32 v45, v50, v51
	v_addc_co_u32_e32 v47, vcc, 0, v123, vcc
	ds_write_b128 v241, v[42:45] offset:8448
	v_pk_add_f32 v[40:41], v[40:41], v[78:79]
	v_pk_add_f32 v[38:39], v[38:39], v[110:111]
	v_pk_add_f32 v[42:43], v[32:33], v[80:81]
	v_pk_add_f32 v[32:33], v[30:31], v[112:113]
	v_lshlrev_b32_e32 v114, 16, v82
	v_and_b32_e32 v115, 0xffff0000, v82
	v_lshlrev_b32_e32 v82, 16, v83
	v_and_b32_e32 v83, 0xffff0000, v83
	v_cvt_pk_bf16_f32 v30, v38, v39
	v_cvt_pk_bf16_f32 v31, v40, v41
	v_cvt_pk_bf16_f32 v32, v32, v33
	v_cvt_pk_bf16_f32 v33, v42, v43
	v_lshlrev_b32_e32 v116, 16, v84
	v_and_b32_e32 v117, 0xffff0000, v84
	v_lshlrev_b32_e32 v84, 16, v85
	v_and_b32_e32 v85, 0xffff0000, v85
	ds_write_b128 v241, v[30:33] offset:8192
	v_lshlrev_b32_e32 v118, 16, v86
	v_and_b32_e32 v119, 0xffff0000, v86
	v_pk_add_f32 v[30:31], v[36:37], v[82:83]
	v_pk_add_f32 v[32:33], v[34:35], v[114:115]
	v_pk_add_f32 v[34:35], v[28:29], v[84:85]
	v_pk_add_f32 v[28:29], v[26:27], v[116:117]
	v_cvt_pk_bf16_f32 v27, v30, v31
	v_add_co_u32_e32 v30, vcc, s45, v122
	v_lshlrev_b32_e32 v86, 16, v87
	v_and_b32_e32 v87, 0xffff0000, v87
	v_lshlrev_b32_e32 v120, 16, v88
	v_and_b32_e32 v121, 0xffff0000, v88
	v_lshlrev_b32_e32 v88, 16, v89
	v_and_b32_e32 v89, 0xffff0000, v89
	v_cvt_pk_bf16_f32 v26, v32, v33
	v_cvt_pk_bf16_f32 v28, v28, v29
	v_cvt_pk_bf16_f32 v29, v34, v35
	v_addc_co_u32_e32 v31, vcc, 0, v123, vcc
	ds_write_b128 v241, v[26:29] offset:16384
	v_pk_add_f32 v[24:25], v[24:25], v[86:87]
	v_pk_add_f32 v[22:23], v[22:23], v[118:119]
	v_pk_add_f32 v[26:27], v[16:17], v[88:89]
	v_pk_add_f32 v[16:17], v[14:15], v[120:121]
	v_lshlrev_b32_e32 v124, 16, v90
	v_and_b32_e32 v125, 0xffff0000, v90
	v_lshlrev_b32_e32 v90, 16, v91
	v_and_b32_e32 v91, 0xffff0000, v91
	v_cvt_pk_bf16_f32 v14, v22, v23
	v_cvt_pk_bf16_f32 v15, v24, v25
	v_cvt_pk_bf16_f32 v16, v16, v17
	v_cvt_pk_bf16_f32 v17, v26, v27
	v_lshlrev_b32_e32 v126, 16, v92
	v_and_b32_e32 v127, 0xffff0000, v92
	v_lshlrev_b32_e32 v92, 16, v93
	v_and_b32_e32 v93, 0xffff0000, v93
	ds_write_b128 v241, v[14:17] offset:16640
	v_lshlrev_b32_e32 v128, 16, v94
	v_and_b32_e32 v129, 0xffff0000, v94
	v_pk_add_f32 v[14:15], v[20:21], v[90:91]
	v_pk_add_f32 v[16:17], v[18:19], v[124:125]
	v_pk_add_f32 v[18:19], v[12:13], v[92:93]
	v_pk_add_f32 v[12:13], v[10:11], v[126:127]
	v_cvt_pk_bf16_f32 v11, v14, v15
	v_add_co_u32_e32 v14, vcc, s46, v122
	v_lshlrev_b32_e32 v94, 16, v95
	v_and_b32_e32 v95, 0xffff0000, v95
	v_lshlrev_b32_e32 v146, 16, v96
	v_and_b32_e32 v147, 0xffff0000, v96
	v_lshlrev_b32_e32 v96, 16, v97
	v_and_b32_e32 v97, 0xffff0000, v97
	v_cvt_pk_bf16_f32 v10, v16, v17
	v_cvt_pk_bf16_f32 v12, v12, v13
	v_cvt_pk_bf16_f32 v13, v18, v19
	v_addc_co_u32_e32 v15, vcc, 0, v123, vcc
	ds_write_b128 v241, v[10:13] offset:24832
	v_pk_add_f32 v[8:9], v[8:9], v[94:95]
	v_pk_add_f32 v[6:7], v[6:7], v[128:129]
	v_pk_add_f32 v[10:11], v[4:5], v[96:97]
	v_pk_add_f32 v[4:5], v[2:3], v[146:147]
	v_cvt_pk_bf16_f32 v2, v6, v7
	v_cvt_pk_bf16_f32 v3, v8, v9
	v_cvt_pk_bf16_f32 v4, v4, v5
	v_cvt_pk_bf16_f32 v5, v10, v11
	ds_write_b128 v241, v[2:5] offset:24576
	s_and_b64 vcc, exec, s[0:1]
	s_cbranch_vccz .LBB0_1186
	s_waitcnt vmcnt(0) lgkmcnt(0)
	s_barrier
	v_cmp_gt_u32_e32 vcc, 0x100, v0
	s_and_saveexec_b64 s[2:3], vcc
	s_cbranch_execz .Lfn_ssq_done
	v_lshlrev_b32_e32 v2, 9, v0
	v_and_b32_e32 v3, 31, v0
	v_lshl_or_b32 v2, v3, 4, v2
	v_mov_b32_e32 v4, 0
	v_mov_b32_e32 v5, 0
	v_mov_b32_e32 v6, 0
	v_mov_b32_e32 v7, 0
	ds_read_b128 v[16:19], v2
	v_xor_b32_e32 v9, 0x10, v2
	ds_read_b128 v[20:23], v9
	v_xor_b32_e32 v10, 0x20, v2
	ds_read_b128 v[24:27], v10
	v_xor_b32_e32 v11, 0x30, v2
	ds_read_b128 v[28:31], v11
	v_xor_b32_e32 v12, 0x40, v2
	ds_read_b128 v[32:35], v12
	v_xor_b32_e32 v13, 0x50, v2
	ds_read_b128 v[36:39], v13
	v_xor_b32_e32 v14, 0x60, v2
	ds_read_b128 v[40:43], v14
	v_xor_b32_e32 v15, 0x70, v2
	ds_read_b128 v[44:47], v15
	s_waitcnt lgkmcnt(0)
	v_lshlrev_b32_e32 v48, 16, v16
	v_and_b32_e32 v49, 0xffff0000, v16
	v_fmac_f32_e32 v4, v48, v48
	v_fmac_f32_e32 v5, v49, v49
	v_lshlrev_b32_e32 v48, 16, v17
	v_and_b32_e32 v49, 0xffff0000, v17
	v_fmac_f32_e32 v6, v48, v48
	v_fmac_f32_e32 v7, v49, v49
	v_lshlrev_b32_e32 v48, 16, v18
	v_and_b32_e32 v49, 0xffff0000, v18
	v_fmac_f32_e32 v4, v48, v48
	v_fmac_f32_e32 v5, v49, v49
	v_lshlrev_b32_e32 v48, 16, v19
	v_and_b32_e32 v49, 0xffff0000, v19
	v_fmac_f32_e32 v6, v48, v48
	v_fmac_f32_e32 v7, v49, v49
	v_lshlrev_b32_e32 v48, 16, v20
	v_and_b32_e32 v49, 0xffff0000, v20
	v_fmac_f32_e32 v4, v48, v48
	v_fmac_f32_e32 v5, v49, v49
	v_lshlrev_b32_e32 v48, 16, v21
	v_and_b32_e32 v49, 0xffff0000, v21
	v_fmac_f32_e32 v6, v48, v48
	v_fmac_f32_e32 v7, v49, v49
	v_lshlrev_b32_e32 v48, 16, v22
	v_and_b32_e32 v49, 0xffff0000, v22
	v_fmac_f32_e32 v4, v48, v48
	v_fmac_f32_e32 v5, v49, v49
	v_lshlrev_b32_e32 v48, 16, v23
	v_and_b32_e32 v49, 0xffff0000, v23
	v_fmac_f32_e32 v6, v48, v48
	v_fmac_f32_e32 v7, v49, v49
	v_lshlrev_b32_e32 v48, 16, v24
	v_and_b32_e32 v49, 0xffff0000, v24
	v_fmac_f32_e32 v4, v48, v48
	v_fmac_f32_e32 v5, v49, v49
	v_lshlrev_b32_e32 v48, 16, v25
	v_and_b32_e32 v49, 0xffff0000, v25
	v_fmac_f32_e32 v6, v48, v48
	v_fmac_f32_e32 v7, v49, v49
	v_lshlrev_b32_e32 v48, 16, v26
	v_and_b32_e32 v49, 0xffff0000, v26
	v_fmac_f32_e32 v4, v48, v48
	v_fmac_f32_e32 v5, v49, v49
	v_lshlrev_b32_e32 v48, 16, v27
	v_and_b32_e32 v49, 0xffff0000, v27
	v_fmac_f32_e32 v6, v48, v48
	v_fmac_f32_e32 v7, v49, v49
	v_lshlrev_b32_e32 v48, 16, v28
	v_and_b32_e32 v49, 0xffff0000, v28
	v_fmac_f32_e32 v4, v48, v48
	v_fmac_f32_e32 v5, v49, v49
	v_lshlrev_b32_e32 v48, 16, v29
	v_and_b32_e32 v49, 0xffff0000, v29
	v_fmac_f32_e32 v6, v48, v48
	v_fmac_f32_e32 v7, v49, v49
	v_lshlrev_b32_e32 v48, 16, v30
	v_and_b32_e32 v49, 0xffff0000, v30
	v_fmac_f32_e32 v4, v48, v48
	v_fmac_f32_e32 v5, v49, v49
	v_lshlrev_b32_e32 v48, 16, v31
	v_and_b32_e32 v49, 0xffff0000, v31
	v_fmac_f32_e32 v6, v48, v48
	v_fmac_f32_e32 v7, v49, v49
	v_lshlrev_b32_e32 v48, 16, v32
	v_and_b32_e32 v49, 0xffff0000, v32
	v_fmac_f32_e32 v4, v48, v48
	v_fmac_f32_e32 v5, v49, v49
	v_lshlrev_b32_e32 v48, 16, v33
	v_and_b32_e32 v49, 0xffff0000, v33
	v_fmac_f32_e32 v6, v48, v48
	v_fmac_f32_e32 v7, v49, v49
	v_lshlrev_b32_e32 v48, 16, v34
	v_and_b32_e32 v49, 0xffff0000, v34
	v_fmac_f32_e32 v4, v48, v48
	v_fmac_f32_e32 v5, v49, v49
	v_lshlrev_b32_e32 v48, 16, v35
	v_and_b32_e32 v49, 0xffff0000, v35
	v_fmac_f32_e32 v6, v48, v48
	v_fmac_f32_e32 v7, v49, v49
	v_lshlrev_b32_e32 v48, 16, v36
	v_and_b32_e32 v49, 0xffff0000, v36
	v_fmac_f32_e32 v4, v48, v48
	v_fmac_f32_e32 v5, v49, v49
	v_lshlrev_b32_e32 v48, 16, v37
	v_and_b32_e32 v49, 0xffff0000, v37
	v_fmac_f32_e32 v6, v48, v48
	v_fmac_f32_e32 v7, v49, v49
	v_lshlrev_b32_e32 v48, 16, v38
	v_and_b32_e32 v49, 0xffff0000, v38
	v_fmac_f32_e32 v4, v48, v48
	v_fmac_f32_e32 v5, v49, v49
	v_lshlrev_b32_e32 v48, 16, v39
	v_and_b32_e32 v49, 0xffff0000, v39
	v_fmac_f32_e32 v6, v48, v48
	v_fmac_f32_e32 v7, v49, v49
	v_lshlrev_b32_e32 v48, 16, v40
	v_and_b32_e32 v49, 0xffff0000, v40
	v_fmac_f32_e32 v4, v48, v48
	v_fmac_f32_e32 v5, v49, v49
	v_lshlrev_b32_e32 v48, 16, v41
	v_and_b32_e32 v49, 0xffff0000, v41
	v_fmac_f32_e32 v6, v48, v48
	v_fmac_f32_e32 v7, v49, v49
	v_lshlrev_b32_e32 v48, 16, v42
	v_and_b32_e32 v49, 0xffff0000, v42
	v_fmac_f32_e32 v4, v48, v48
	v_fmac_f32_e32 v5, v49, v49
	v_lshlrev_b32_e32 v48, 16, v43
	v_and_b32_e32 v49, 0xffff0000, v43
	v_fmac_f32_e32 v6, v48, v48
	v_fmac_f32_e32 v7, v49, v49
	v_lshlrev_b32_e32 v48, 16, v44
	v_and_b32_e32 v49, 0xffff0000, v44
	v_fmac_f32_e32 v4, v48, v48
	v_fmac_f32_e32 v5, v49, v49
	v_lshlrev_b32_e32 v48, 16, v45
	v_and_b32_e32 v49, 0xffff0000, v45
	v_fmac_f32_e32 v6, v48, v48
	v_fmac_f32_e32 v7, v49, v49
	v_lshlrev_b32_e32 v48, 16, v46
	v_and_b32_e32 v49, 0xffff0000, v46
	v_fmac_f32_e32 v4, v48, v48
	v_fmac_f32_e32 v5, v49, v49
	v_lshlrev_b32_e32 v48, 16, v47
	v_and_b32_e32 v49, 0xffff0000, v47
	v_fmac_f32_e32 v6, v48, v48
	v_fmac_f32_e32 v7, v49, v49
	v_xor_b32_e32 v8, 0x80, v2
	ds_read_b128 v[16:19], v8
	v_xor_b32_e32 v9, 0x90, v2
	ds_read_b128 v[20:23], v9
	v_xor_b32_e32 v10, 0xa0, v2
	ds_read_b128 v[24:27], v10
	v_xor_b32_e32 v11, 0xb0, v2
	ds_read_b128 v[28:31], v11
	v_xor_b32_e32 v12, 0xc0, v2
	ds_read_b128 v[32:35], v12
	v_xor_b32_e32 v13, 0xd0, v2
	ds_read_b128 v[36:39], v13
	v_xor_b32_e32 v14, 0xe0, v2
	ds_read_b128 v[40:43], v14
	v_xor_b32_e32 v15, 0xf0, v2
	ds_read_b128 v[44:47], v15
	s_waitcnt lgkmcnt(0)
	v_lshlrev_b32_e32 v48, 16, v16
	v_and_b32_e32 v49, 0xffff0000, v16
	v_fmac_f32_e32 v4, v48, v48
	v_fmac_f32_e32 v5, v49, v49
	v_lshlrev_b32_e32 v48, 16, v17
	v_and_b32_e32 v49, 0xffff0000, v17
	v_fmac_f32_e32 v6, v48, v48
	v_fmac_f32_e32 v7, v49, v49
	v_lshlrev_b32_e32 v48, 16, v18
	v_and_b32_e32 v49, 0xffff0000, v18
	v_fmac_f32_e32 v4, v48, v48
	v_fmac_f32_e32 v5, v49, v49
	v_lshlrev_b32_e32 v48, 16, v19
	v_and_b32_e32 v49, 0xffff0000, v19
	v_fmac_f32_e32 v6, v48, v48
	v_fmac_f32_e32 v7, v49, v49
	v_lshlrev_b32_e32 v48, 16, v20
	v_and_b32_e32 v49, 0xffff0000, v20
	v_fmac_f32_e32 v4, v48, v48
	v_fmac_f32_e32 v5, v49, v49
	v_lshlrev_b32_e32 v48, 16, v21
	v_and_b32_e32 v49, 0xffff0000, v21
	v_fmac_f32_e32 v6, v48, v48
	v_fmac_f32_e32 v7, v49, v49
	v_lshlrev_b32_e32 v48, 16, v22
	v_and_b32_e32 v49, 0xffff0000, v22
	v_fmac_f32_e32 v4, v48, v48
	v_fmac_f32_e32 v5, v49, v49
	v_lshlrev_b32_e32 v48, 16, v23
	v_and_b32_e32 v49, 0xffff0000, v23
	v_fmac_f32_e32 v6, v48, v48
	v_fmac_f32_e32 v7, v49, v49
	v_lshlrev_b32_e32 v48, 16, v24
	v_and_b32_e32 v49, 0xffff0000, v24
	v_fmac_f32_e32 v4, v48, v48
	v_fmac_f32_e32 v5, v49, v49
	v_lshlrev_b32_e32 v48, 16, v25
	v_and_b32_e32 v49, 0xffff0000, v25
	v_fmac_f32_e32 v6, v48, v48
	v_fmac_f32_e32 v7, v49, v49
	v_lshlrev_b32_e32 v48, 16, v26
	v_and_b32_e32 v49, 0xffff0000, v26
	v_fmac_f32_e32 v4, v48, v48
	v_fmac_f32_e32 v5, v49, v49
	v_lshlrev_b32_e32 v48, 16, v27
	v_and_b32_e32 v49, 0xffff0000, v27
	v_fmac_f32_e32 v6, v48, v48
	v_fmac_f32_e32 v7, v49, v49
	v_lshlrev_b32_e32 v48, 16, v28
	v_and_b32_e32 v49, 0xffff0000, v28
	v_fmac_f32_e32 v4, v48, v48
	v_fmac_f32_e32 v5, v49, v49
	v_lshlrev_b32_e32 v48, 16, v29
	v_and_b32_e32 v49, 0xffff0000, v29
	v_fmac_f32_e32 v6, v48, v48
	v_fmac_f32_e32 v7, v49, v49
	v_lshlrev_b32_e32 v48, 16, v30
	v_and_b32_e32 v49, 0xffff0000, v30
	v_fmac_f32_e32 v4, v48, v48
	v_fmac_f32_e32 v5, v49, v49
	v_lshlrev_b32_e32 v48, 16, v31
	v_and_b32_e32 v49, 0xffff0000, v31
	v_fmac_f32_e32 v6, v48, v48
	v_fmac_f32_e32 v7, v49, v49
	v_lshlrev_b32_e32 v48, 16, v32
	v_and_b32_e32 v49, 0xffff0000, v32
	v_fmac_f32_e32 v4, v48, v48
	v_fmac_f32_e32 v5, v49, v49
	v_lshlrev_b32_e32 v48, 16, v33
	v_and_b32_e32 v49, 0xffff0000, v33
	v_fmac_f32_e32 v6, v48, v48
	v_fmac_f32_e32 v7, v49, v49
	v_lshlrev_b32_e32 v48, 16, v34
	v_and_b32_e32 v49, 0xffff0000, v34
	v_fmac_f32_e32 v4, v48, v48
	v_fmac_f32_e32 v5, v49, v49
	v_lshlrev_b32_e32 v48, 16, v35
	v_and_b32_e32 v49, 0xffff0000, v35
	v_fmac_f32_e32 v6, v48, v48
	v_fmac_f32_e32 v7, v49, v49
	v_lshlrev_b32_e32 v48, 16, v36
	v_and_b32_e32 v49, 0xffff0000, v36
	v_fmac_f32_e32 v4, v48, v48
	v_fmac_f32_e32 v5, v49, v49
	v_lshlrev_b32_e32 v48, 16, v37
	v_and_b32_e32 v49, 0xffff0000, v37
	v_fmac_f32_e32 v6, v48, v48
	v_fmac_f32_e32 v7, v49, v49
	v_lshlrev_b32_e32 v48, 16, v38
	v_and_b32_e32 v49, 0xffff0000, v38
	v_fmac_f32_e32 v4, v48, v48
	v_fmac_f32_e32 v5, v49, v49
	v_lshlrev_b32_e32 v48, 16, v39
	v_and_b32_e32 v49, 0xffff0000, v39
	v_fmac_f32_e32 v6, v48, v48
	v_fmac_f32_e32 v7, v49, v49
	v_lshlrev_b32_e32 v48, 16, v40
	v_and_b32_e32 v49, 0xffff0000, v40
	v_fmac_f32_e32 v4, v48, v48
	v_fmac_f32_e32 v5, v49, v49
	v_lshlrev_b32_e32 v48, 16, v41
	v_and_b32_e32 v49, 0xffff0000, v41
	v_fmac_f32_e32 v6, v48, v48
	v_fmac_f32_e32 v7, v49, v49
	v_lshlrev_b32_e32 v48, 16, v42
	v_and_b32_e32 v49, 0xffff0000, v42
	v_fmac_f32_e32 v4, v48, v48
	v_fmac_f32_e32 v5, v49, v49
	v_lshlrev_b32_e32 v48, 16, v43
	v_and_b32_e32 v49, 0xffff0000, v43
	v_fmac_f32_e32 v6, v48, v48
	v_fmac_f32_e32 v7, v49, v49
	v_lshlrev_b32_e32 v48, 16, v44
	v_and_b32_e32 v49, 0xffff0000, v44
	v_fmac_f32_e32 v4, v48, v48
	v_fmac_f32_e32 v5, v49, v49
	v_lshlrev_b32_e32 v48, 16, v45
	v_and_b32_e32 v49, 0xffff0000, v45
	v_fmac_f32_e32 v6, v48, v48
	v_fmac_f32_e32 v7, v49, v49
	v_lshlrev_b32_e32 v48, 16, v46
	v_and_b32_e32 v49, 0xffff0000, v46
	v_fmac_f32_e32 v4, v48, v48
	v_fmac_f32_e32 v5, v49, v49
	v_lshlrev_b32_e32 v48, 16, v47
	v_and_b32_e32 v49, 0xffff0000, v47
	v_fmac_f32_e32 v6, v48, v48
	v_fmac_f32_e32 v7, v49, v49
	v_xor_b32_e32 v8, 0x100, v2
	ds_read_b128 v[16:19], v8
	v_xor_b32_e32 v9, 0x110, v2
	ds_read_b128 v[20:23], v9
	v_xor_b32_e32 v10, 0x120, v2
	ds_read_b128 v[24:27], v10
	v_xor_b32_e32 v11, 0x130, v2
	ds_read_b128 v[28:31], v11
	v_xor_b32_e32 v12, 0x140, v2
	ds_read_b128 v[32:35], v12
	v_xor_b32_e32 v13, 0x150, v2
	ds_read_b128 v[36:39], v13
	v_xor_b32_e32 v14, 0x160, v2
	ds_read_b128 v[40:43], v14
	v_xor_b32_e32 v15, 0x170, v2
	ds_read_b128 v[44:47], v15
	s_waitcnt lgkmcnt(0)
	v_lshlrev_b32_e32 v48, 16, v16
	v_and_b32_e32 v49, 0xffff0000, v16
	v_fmac_f32_e32 v4, v48, v48
	v_fmac_f32_e32 v5, v49, v49
	v_lshlrev_b32_e32 v48, 16, v17
	v_and_b32_e32 v49, 0xffff0000, v17
	v_fmac_f32_e32 v6, v48, v48
	v_fmac_f32_e32 v7, v49, v49
	v_lshlrev_b32_e32 v48, 16, v18
	v_and_b32_e32 v49, 0xffff0000, v18
	v_fmac_f32_e32 v4, v48, v48
	v_fmac_f32_e32 v5, v49, v49
	v_lshlrev_b32_e32 v48, 16, v19
	v_and_b32_e32 v49, 0xffff0000, v19
	v_fmac_f32_e32 v6, v48, v48
	v_fmac_f32_e32 v7, v49, v49
	v_lshlrev_b32_e32 v48, 16, v20
	v_and_b32_e32 v49, 0xffff0000, v20
	v_fmac_f32_e32 v4, v48, v48
	v_fmac_f32_e32 v5, v49, v49
	v_lshlrev_b32_e32 v48, 16, v21
	v_and_b32_e32 v49, 0xffff0000, v21
	v_fmac_f32_e32 v6, v48, v48
	v_fmac_f32_e32 v7, v49, v49
	v_lshlrev_b32_e32 v48, 16, v22
	v_and_b32_e32 v49, 0xffff0000, v22
	v_fmac_f32_e32 v4, v48, v48
	v_fmac_f32_e32 v5, v49, v49
	v_lshlrev_b32_e32 v48, 16, v23
	v_and_b32_e32 v49, 0xffff0000, v23
	v_fmac_f32_e32 v6, v48, v48
	v_fmac_f32_e32 v7, v49, v49
	v_lshlrev_b32_e32 v48, 16, v24
	v_and_b32_e32 v49, 0xffff0000, v24
	v_fmac_f32_e32 v4, v48, v48
	v_fmac_f32_e32 v5, v49, v49
	v_lshlrev_b32_e32 v48, 16, v25
	v_and_b32_e32 v49, 0xffff0000, v25
	v_fmac_f32_e32 v6, v48, v48
	v_fmac_f32_e32 v7, v49, v49
	v_lshlrev_b32_e32 v48, 16, v26
	v_and_b32_e32 v49, 0xffff0000, v26
	v_fmac_f32_e32 v4, v48, v48
	v_fmac_f32_e32 v5, v49, v49
	v_lshlrev_b32_e32 v48, 16, v27
	v_and_b32_e32 v49, 0xffff0000, v27
	v_fmac_f32_e32 v6, v48, v48
	v_fmac_f32_e32 v7, v49, v49
	v_lshlrev_b32_e32 v48, 16, v28
	v_and_b32_e32 v49, 0xffff0000, v28
	v_fmac_f32_e32 v4, v48, v48
	v_fmac_f32_e32 v5, v49, v49
	v_lshlrev_b32_e32 v48, 16, v29
	v_and_b32_e32 v49, 0xffff0000, v29
	v_fmac_f32_e32 v6, v48, v48
	v_fmac_f32_e32 v7, v49, v49
	v_lshlrev_b32_e32 v48, 16, v30
	v_and_b32_e32 v49, 0xffff0000, v30
	v_fmac_f32_e32 v4, v48, v48
	v_fmac_f32_e32 v5, v49, v49
	v_lshlrev_b32_e32 v48, 16, v31
	v_and_b32_e32 v49, 0xffff0000, v31
	v_fmac_f32_e32 v6, v48, v48
	v_fmac_f32_e32 v7, v49, v49
	v_lshlrev_b32_e32 v48, 16, v32
	v_and_b32_e32 v49, 0xffff0000, v32
	v_fmac_f32_e32 v4, v48, v48
	v_fmac_f32_e32 v5, v49, v49
	v_lshlrev_b32_e32 v48, 16, v33
	v_and_b32_e32 v49, 0xffff0000, v33
	v_fmac_f32_e32 v6, v48, v48
	v_fmac_f32_e32 v7, v49, v49
	v_lshlrev_b32_e32 v48, 16, v34
	v_and_b32_e32 v49, 0xffff0000, v34
	v_fmac_f32_e32 v4, v48, v48
	v_fmac_f32_e32 v5, v49, v49
	v_lshlrev_b32_e32 v48, 16, v35
	v_and_b32_e32 v49, 0xffff0000, v35
	v_fmac_f32_e32 v6, v48, v48
	v_fmac_f32_e32 v7, v49, v49
	v_lshlrev_b32_e32 v48, 16, v36
	v_and_b32_e32 v49, 0xffff0000, v36
	v_fmac_f32_e32 v4, v48, v48
	v_fmac_f32_e32 v5, v49, v49
	v_lshlrev_b32_e32 v48, 16, v37
	v_and_b32_e32 v49, 0xffff0000, v37
	v_fmac_f32_e32 v6, v48, v48
	v_fmac_f32_e32 v7, v49, v49
	v_lshlrev_b32_e32 v48, 16, v38
	v_and_b32_e32 v49, 0xffff0000, v38
	v_fmac_f32_e32 v4, v48, v48
	v_fmac_f32_e32 v5, v49, v49
	v_lshlrev_b32_e32 v48, 16, v39
	v_and_b32_e32 v49, 0xffff0000, v39
	v_fmac_f32_e32 v6, v48, v48
	v_fmac_f32_e32 v7, v49, v49
	v_lshlrev_b32_e32 v48, 16, v40
	v_and_b32_e32 v49, 0xffff0000, v40
	v_fmac_f32_e32 v4, v48, v48
	v_fmac_f32_e32 v5, v49, v49
	v_lshlrev_b32_e32 v48, 16, v41
	v_and_b32_e32 v49, 0xffff0000, v41
	v_fmac_f32_e32 v6, v48, v48
	v_fmac_f32_e32 v7, v49, v49
	v_lshlrev_b32_e32 v48, 16, v42
	v_and_b32_e32 v49, 0xffff0000, v42
	v_fmac_f32_e32 v4, v48, v48
	v_fmac_f32_e32 v5, v49, v49
	v_lshlrev_b32_e32 v48, 16, v43
	v_and_b32_e32 v49, 0xffff0000, v43
	v_fmac_f32_e32 v6, v48, v48
	v_fmac_f32_e32 v7, v49, v49
	v_lshlrev_b32_e32 v48, 16, v44
	v_and_b32_e32 v49, 0xffff0000, v44
	v_fmac_f32_e32 v4, v48, v48
	v_fmac_f32_e32 v5, v49, v49
	v_lshlrev_b32_e32 v48, 16, v45
	v_and_b32_e32 v49, 0xffff0000, v45
	v_fmac_f32_e32 v6, v48, v48
	v_fmac_f32_e32 v7, v49, v49
	v_lshlrev_b32_e32 v48, 16, v46
	v_and_b32_e32 v49, 0xffff0000, v46
	v_fmac_f32_e32 v4, v48, v48
	v_fmac_f32_e32 v5, v49, v49
	v_lshlrev_b32_e32 v48, 16, v47
	v_and_b32_e32 v49, 0xffff0000, v47
	v_fmac_f32_e32 v6, v48, v48
	v_fmac_f32_e32 v7, v49, v49
	v_xor_b32_e32 v8, 0x180, v2
	ds_read_b128 v[16:19], v8
	v_xor_b32_e32 v9, 0x190, v2
	ds_read_b128 v[20:23], v9
	v_xor_b32_e32 v10, 0x1a0, v2
	ds_read_b128 v[24:27], v10
	v_xor_b32_e32 v11, 0x1b0, v2
	ds_read_b128 v[28:31], v11
	v_xor_b32_e32 v12, 0x1c0, v2
	ds_read_b128 v[32:35], v12
	v_xor_b32_e32 v13, 0x1d0, v2
	ds_read_b128 v[36:39], v13
	v_xor_b32_e32 v14, 0x1e0, v2
	ds_read_b128 v[40:43], v14
	v_xor_b32_e32 v15, 0x1f0, v2
	ds_read_b128 v[44:47], v15
	s_waitcnt lgkmcnt(0)
	v_lshlrev_b32_e32 v48, 16, v16
	v_and_b32_e32 v49, 0xffff0000, v16
	v_fmac_f32_e32 v4, v48, v48
	v_fmac_f32_e32 v5, v49, v49
	v_lshlrev_b32_e32 v48, 16, v17
	v_and_b32_e32 v49, 0xffff0000, v17
	v_fmac_f32_e32 v6, v48, v48
	v_fmac_f32_e32 v7, v49, v49
	v_lshlrev_b32_e32 v48, 16, v18
	v_and_b32_e32 v49, 0xffff0000, v18
	v_fmac_f32_e32 v4, v48, v48
	v_fmac_f32_e32 v5, v49, v49
	v_lshlrev_b32_e32 v48, 16, v19
	v_and_b32_e32 v49, 0xffff0000, v19
	v_fmac_f32_e32 v6, v48, v48
	v_fmac_f32_e32 v7, v49, v49
	v_lshlrev_b32_e32 v48, 16, v20
	v_and_b32_e32 v49, 0xffff0000, v20
	v_fmac_f32_e32 v4, v48, v48
	v_fmac_f32_e32 v5, v49, v49
	v_lshlrev_b32_e32 v48, 16, v21
	v_and_b32_e32 v49, 0xffff0000, v21
	v_fmac_f32_e32 v6, v48, v48
	v_fmac_f32_e32 v7, v49, v49
	v_lshlrev_b32_e32 v48, 16, v22
	v_and_b32_e32 v49, 0xffff0000, v22
	v_fmac_f32_e32 v4, v48, v48
	v_fmac_f32_e32 v5, v49, v49
	v_lshlrev_b32_e32 v48, 16, v23
	v_and_b32_e32 v49, 0xffff0000, v23
	v_fmac_f32_e32 v6, v48, v48
	v_fmac_f32_e32 v7, v49, v49
	v_lshlrev_b32_e32 v48, 16, v24
	v_and_b32_e32 v49, 0xffff0000, v24
	v_fmac_f32_e32 v4, v48, v48
	v_fmac_f32_e32 v5, v49, v49
	v_lshlrev_b32_e32 v48, 16, v25
	v_and_b32_e32 v49, 0xffff0000, v25
	v_fmac_f32_e32 v6, v48, v48
	v_fmac_f32_e32 v7, v49, v49
	v_lshlrev_b32_e32 v48, 16, v26
	v_and_b32_e32 v49, 0xffff0000, v26
	v_fmac_f32_e32 v4, v48, v48
	v_fmac_f32_e32 v5, v49, v49
	v_lshlrev_b32_e32 v48, 16, v27
	v_and_b32_e32 v49, 0xffff0000, v27
	v_fmac_f32_e32 v6, v48, v48
	v_fmac_f32_e32 v7, v49, v49
	v_lshlrev_b32_e32 v48, 16, v28
	v_and_b32_e32 v49, 0xffff0000, v28
	v_fmac_f32_e32 v4, v48, v48
	v_fmac_f32_e32 v5, v49, v49
	v_lshlrev_b32_e32 v48, 16, v29
	v_and_b32_e32 v49, 0xffff0000, v29
	v_fmac_f32_e32 v6, v48, v48
	v_fmac_f32_e32 v7, v49, v49
	v_lshlrev_b32_e32 v48, 16, v30
	v_and_b32_e32 v49, 0xffff0000, v30
	v_fmac_f32_e32 v4, v48, v48
	v_fmac_f32_e32 v5, v49, v49
	v_lshlrev_b32_e32 v48, 16, v31
	v_and_b32_e32 v49, 0xffff0000, v31
	v_fmac_f32_e32 v6, v48, v48
	v_fmac_f32_e32 v7, v49, v49
	v_lshlrev_b32_e32 v48, 16, v32
	v_and_b32_e32 v49, 0xffff0000, v32
	v_fmac_f32_e32 v4, v48, v48
	v_fmac_f32_e32 v5, v49, v49
	v_lshlrev_b32_e32 v48, 16, v33
	v_and_b32_e32 v49, 0xffff0000, v33
	v_fmac_f32_e32 v6, v48, v48
	v_fmac_f32_e32 v7, v49, v49
	v_lshlrev_b32_e32 v48, 16, v34
	v_and_b32_e32 v49, 0xffff0000, v34
	v_fmac_f32_e32 v4, v48, v48
	v_fmac_f32_e32 v5, v49, v49
	v_lshlrev_b32_e32 v48, 16, v35
	v_and_b32_e32 v49, 0xffff0000, v35
	v_fmac_f32_e32 v6, v48, v48
	v_fmac_f32_e32 v7, v49, v49
	v_lshlrev_b32_e32 v48, 16, v36
	v_and_b32_e32 v49, 0xffff0000, v36
	v_fmac_f32_e32 v4, v48, v48
	v_fmac_f32_e32 v5, v49, v49
	v_lshlrev_b32_e32 v48, 16, v37
	v_and_b32_e32 v49, 0xffff0000, v37
	v_fmac_f32_e32 v6, v48, v48
	v_fmac_f32_e32 v7, v49, v49
	v_lshlrev_b32_e32 v48, 16, v38
	v_and_b32_e32 v49, 0xffff0000, v38
	v_fmac_f32_e32 v4, v48, v48
	v_fmac_f32_e32 v5, v49, v49
	v_lshlrev_b32_e32 v48, 16, v39
	v_and_b32_e32 v49, 0xffff0000, v39
	v_fmac_f32_e32 v6, v48, v48
	v_fmac_f32_e32 v7, v49, v49
	v_lshlrev_b32_e32 v48, 16, v40
	v_and_b32_e32 v49, 0xffff0000, v40
	v_fmac_f32_e32 v4, v48, v48
	v_fmac_f32_e32 v5, v49, v49
	v_lshlrev_b32_e32 v48, 16, v41
	v_and_b32_e32 v49, 0xffff0000, v41
	v_fmac_f32_e32 v6, v48, v48
	v_fmac_f32_e32 v7, v49, v49
	v_lshlrev_b32_e32 v48, 16, v42
	v_and_b32_e32 v49, 0xffff0000, v42
	v_fmac_f32_e32 v4, v48, v48
	v_fmac_f32_e32 v5, v49, v49
	v_lshlrev_b32_e32 v48, 16, v43
	v_and_b32_e32 v49, 0xffff0000, v43
	v_fmac_f32_e32 v6, v48, v48
	v_fmac_f32_e32 v7, v49, v49
	v_lshlrev_b32_e32 v48, 16, v44
	v_and_b32_e32 v49, 0xffff0000, v44
	v_fmac_f32_e32 v4, v48, v48
	v_fmac_f32_e32 v5, v49, v49
	v_lshlrev_b32_e32 v48, 16, v45
	v_and_b32_e32 v49, 0xffff0000, v45
	v_fmac_f32_e32 v6, v48, v48
	v_fmac_f32_e32 v7, v49, v49
	v_lshlrev_b32_e32 v48, 16, v46
	v_and_b32_e32 v49, 0xffff0000, v46
	v_fmac_f32_e32 v4, v48, v48
	v_fmac_f32_e32 v5, v49, v49
	v_lshlrev_b32_e32 v48, 16, v47
	v_and_b32_e32 v49, 0xffff0000, v47
	v_fmac_f32_e32 v6, v48, v48
	v_fmac_f32_e32 v7, v49, v49
	v_add_f32_e32 v4, v4, v5
	v_add_f32_e32 v6, v6, v7
	v_add_f32_e32 v4, v4, v6
	s_lshl_b32 s4, s100, 2
	s_add_u32 s4, s4, s101
	s_lshl_b32 s4, s4, 10
	s_add_u32 s4, s4, 0xe000000
	s_add_u32 s0, s94, s4
	s_addc_u32 s1, s95, 0
	v_lshlrev_b32_e32 v8, 2, v0
	global_store_dword v8, v4, s[0:1] sc0 sc1
.Lfn_ssq_done:
	s_or_b64 exec, exec, s[2:3]
	s_waitcnt vmcnt(0)
	s_barrier
	v_cmp_eq_u32_e32 vcc, 0, v0
	s_and_saveexec_b64 s[2:3], vcc
	s_cbranch_execz .Lfn_sync_done
	s_lshl_b32 s4, s100, 2
	s_add_u32 s4, s4, 0xb3d2400
	s_add_u32 s0, s94, s4
	s_addc_u32 s1, s95, 0
	buffer_wbl2 sc1
	s_waitcnt vmcnt(0)
	v_mov_b32_e32 v8, 0
	v_mov_b32_e32 v9, 1
	global_atomic_add v8, v9, s[0:1]
	s_mov_b32 s4, 0
.Lfn_spin:
	global_load_dword v10, v8, s[0:1] sc1
	s_waitcnt vmcnt(0)
	v_cmp_gt_u32_e32 vcc, 4, v10
	s_cbranch_vccz .Lfn_spin_exit
	s_sleep 2
	s_add_u32 s4, s4, 1
	s_cmp_lt_u32 s4, 0x8000
	s_cbranch_scc1 .Lfn_spin
.Lfn_spin_exit:
	s_waitcnt vmcnt(0)
	buffer_inv sc1
	s_waitcnt vmcnt(0)
.Lfn_sync_done:
	s_or_b64 exec, exec, s[2:3]
	s_barrier
	v_cmp_gt_u32_e32 vcc, 0x100, v0
	s_and_saveexec_b64 s[2:3], vcc
	s_cbranch_execz .Lfn_rstd_done
	s_lshl_b32 s4, s100, 12
	s_add_u32 s4, s4, 0xe000000
	s_add_u32 s0, s94, s4
	s_addc_u32 s1, s95, 0
	v_lshlrev_b32_e32 v8, 2, v0
	global_load_dword v10, v8, s[0:1] sc0 sc1
	global_load_dword v11, v8, s[0:1] offset:1024 sc0 sc1
	global_load_dword v12, v8, s[0:1] offset:2048 sc0 sc1
	global_load_dword v13, v8, s[0:1] offset:3072 sc0 sc1
	s_waitcnt vmcnt(0)
	v_add_f32_e32 v10, v10, v11
	v_add_f32_e32 v10, v10, v12
	v_add_f32_e32 v10, v10, v13
	v_mov_b32_e32 v14, 0x3727c5ac
	v_fmamk_f32 v10, v10, 0x3a800000, v14
	v_mul_f32_e32 v11, 0x4b800000, v10
	s_mov_b32 s4, 0x800000
	v_cmp_gt_f32_e32 vcc, s4, v10
	s_nop 1
	v_cndmask_b32_e32 v10, v10, v11, vcc
	v_rsq_f32_e32 v11, v10
	s_nop 0
	v_mul_f32_e32 v12, 0x45800000, v11
	v_cndmask_b32_e32 v11, v11, v12, vcc
	v_add_u32_e32 v8, 0x20010, v8
	ds_write_b32 v8, v11
.Lfn_rstd_done:
	s_or_b64 exec, exec, s[2:3]
	s_waitcnt lgkmcnt(0)
	s_barrier
	v_readfirstlane_b32 s5, v0
	s_lshr_b32 s5, s5, 6
	v_and_b32_e32 v2, 63, v0
	v_lshrrev_b32_e32 v3, 1, v2
	v_and_b32_e32 v9, 1, v2
	v_lshlrev_b32_e32 v3, 4, v3
	v_lshl_or_b32 v3, v9, 3, v3
	s_lshl_b32 s4, s5, 14
	v_add_u32_e32 v3, s4, v3
	v_and_b32_e32 v9, 31, v2
	s_lshl_b32 s4, s5, 5
	v_add_u32_e32 v9, s4, v9
	v_lshlrev_b32_e32 v9, 2, v9
	v_add_u32_e32 v9, 0x20010, v9
	ds_read_b32 v15, v9
	v_lshlrev_b32_e32 v8, 4, v2
	s_lshl_b32 s4, s101, 10
	v_add_u32_e32 v9, s4, v8
	global_load_dwordx4 v[4:7], v9, s[90:91]
	s_lshl_b32 s4, s100, 8
	s_lshl_b32 s0, s5, 5
	s_add_u32 s4, s4, s0
	s_lshl_b32 s4, s4, 12
	s_lshl_b32 s0, s101, 10
	s_add_u32 s4, s4, s0
	s_add_u32 s0, s92, s4
	s_addc_u32 s1, s93, 0
	s_waitcnt vmcnt(0) lgkmcnt(0)
	ds_read_b64 v[16:17], v3
	v_xor_b32_e32 v49, 0x10, v3
	ds_read_b64 v[18:19], v49 offset:512
	v_xor_b32_e32 v50, 0x20, v3
	ds_read_b64 v[20:21], v50 offset:1024
	v_xor_b32_e32 v51, 0x30, v3
	ds_read_b64 v[22:23], v51 offset:1536
	v_xor_b32_e32 v52, 0x40, v3
	ds_read_b64 v[24:25], v52 offset:2048
	v_xor_b32_e32 v53, 0x50, v3
	ds_read_b64 v[26:27], v53 offset:2560
	v_xor_b32_e32 v54, 0x60, v3
	ds_read_b64 v[28:29], v54 offset:3072
	v_xor_b32_e32 v55, 0x70, v3
	ds_read_b64 v[30:31], v55 offset:3584
	s_waitcnt lgkmcnt(0)
	v_readlane_b32 s4, v15, 0
	v_lshlrev_b32_e32 v32, 16, v16
	v_and_b32_e32 v33, 0xffff0000, v16
	v_lshlrev_b32_e32 v34, 16, v17
	v_and_b32_e32 v35, 0xffff0000, v17
	v_mul_f32_e32 v32, s4, v32
	v_mul_f32_e32 v33, s4, v33
	v_mul_f32_e32 v34, s4, v34
	v_mul_f32_e32 v35, s4, v35
	v_mul_f32_e32 v32, v4, v32
	v_mul_f32_e32 v33, v5, v33
	v_mul_f32_e32 v34, v6, v34
	v_mul_f32_e32 v35, v7, v35
	global_store_dwordx4 v8, v[32:35], s[0:1] nt
	s_add_u32 s0, s0, 0x1000
	s_addc_u32 s1, s1, 0
	v_readlane_b32 s4, v15, 1
	v_lshlrev_b32_e32 v36, 16, v18
	v_and_b32_e32 v37, 0xffff0000, v18
	v_lshlrev_b32_e32 v38, 16, v19
	v_and_b32_e32 v39, 0xffff0000, v19
	v_mul_f32_e32 v36, s4, v36
	v_mul_f32_e32 v37, s4, v37
	v_mul_f32_e32 v38, s4, v38
	v_mul_f32_e32 v39, s4, v39
	v_mul_f32_e32 v36, v4, v36
	v_mul_f32_e32 v37, v5, v37
	v_mul_f32_e32 v38, v6, v38
	v_mul_f32_e32 v39, v7, v39
	global_store_dwordx4 v8, v[36:39], s[0:1] nt
	s_add_u32 s0, s0, 0x1000
	s_addc_u32 s1, s1, 0
	v_readlane_b32 s4, v15, 2
	v_lshlrev_b32_e32 v40, 16, v20
	v_and_b32_e32 v41, 0xffff0000, v20
	v_lshlrev_b32_e32 v42, 16, v21
	v_and_b32_e32 v43, 0xffff0000, v21
	v_mul_f32_e32 v40, s4, v40
	v_mul_f32_e32 v41, s4, v41
	v_mul_f32_e32 v42, s4, v42
	v_mul_f32_e32 v43, s4, v43
	v_mul_f32_e32 v40, v4, v40
	v_mul_f32_e32 v41, v5, v41
	v_mul_f32_e32 v42, v6, v42
	v_mul_f32_e32 v43, v7, v43
	global_store_dwordx4 v8, v[40:43], s[0:1] nt
	s_add_u32 s0, s0, 0x1000
	s_addc_u32 s1, s1, 0
	v_readlane_b32 s4, v15, 3
	v_lshlrev_b32_e32 v44, 16, v22
	v_and_b32_e32 v45, 0xffff0000, v22
	v_lshlrev_b32_e32 v46, 16, v23
	v_and_b32_e32 v47, 0xffff0000, v23
	v_mul_f32_e32 v44, s4, v44
	v_mul_f32_e32 v45, s4, v45
	v_mul_f32_e32 v46, s4, v46
	v_mul_f32_e32 v47, s4, v47
	v_mul_f32_e32 v44, v4, v44
	v_mul_f32_e32 v45, v5, v45
	v_mul_f32_e32 v46, v6, v46
	v_mul_f32_e32 v47, v7, v47
	global_store_dwordx4 v8, v[44:47], s[0:1] nt
	s_add_u32 s0, s0, 0x1000
	s_addc_u32 s1, s1, 0
	v_readlane_b32 s4, v15, 4
	v_lshlrev_b32_e32 v32, 16, v24
	v_and_b32_e32 v33, 0xffff0000, v24
	v_lshlrev_b32_e32 v34, 16, v25
	v_and_b32_e32 v35, 0xffff0000, v25
	v_mul_f32_e32 v32, s4, v32
	v_mul_f32_e32 v33, s4, v33
	v_mul_f32_e32 v34, s4, v34
	v_mul_f32_e32 v35, s4, v35
	v_mul_f32_e32 v32, v4, v32
	v_mul_f32_e32 v33, v5, v33
	v_mul_f32_e32 v34, v6, v34
	v_mul_f32_e32 v35, v7, v35
	global_store_dwordx4 v8, v[32:35], s[0:1] nt
	s_add_u32 s0, s0, 0x1000
	s_addc_u32 s1, s1, 0
	v_readlane_b32 s4, v15, 5
	v_lshlrev_b32_e32 v36, 16, v26
	v_and_b32_e32 v37, 0xffff0000, v26
	v_lshlrev_b32_e32 v38, 16, v27
	v_and_b32_e32 v39, 0xffff0000, v27
	v_mul_f32_e32 v36, s4, v36
	v_mul_f32_e32 v37, s4, v37
	v_mul_f32_e32 v38, s4, v38
	v_mul_f32_e32 v39, s4, v39
	v_mul_f32_e32 v36, v4, v36
	v_mul_f32_e32 v37, v5, v37
	v_mul_f32_e32 v38, v6, v38
	v_mul_f32_e32 v39, v7, v39
	global_store_dwordx4 v8, v[36:39], s[0:1] nt
	s_add_u32 s0, s0, 0x1000
	s_addc_u32 s1, s1, 0
	v_readlane_b32 s4, v15, 6
	v_lshlrev_b32_e32 v40, 16, v28
	v_and_b32_e32 v41, 0xffff0000, v28
	v_lshlrev_b32_e32 v42, 16, v29
	v_and_b32_e32 v43, 0xffff0000, v29
	v_mul_f32_e32 v40, s4, v40
	v_mul_f32_e32 v41, s4, v41
	v_mul_f32_e32 v42, s4, v42
	v_mul_f32_e32 v43, s4, v43
	v_mul_f32_e32 v40, v4, v40
	v_mul_f32_e32 v41, v5, v41
	v_mul_f32_e32 v42, v6, v42
	v_mul_f32_e32 v43, v7, v43
	global_store_dwordx4 v8, v[40:43], s[0:1] nt
	s_add_u32 s0, s0, 0x1000
	s_addc_u32 s1, s1, 0
	v_readlane_b32 s4, v15, 7
	v_lshlrev_b32_e32 v44, 16, v30
	v_and_b32_e32 v45, 0xffff0000, v30
	v_lshlrev_b32_e32 v46, 16, v31
	v_and_b32_e32 v47, 0xffff0000, v31
	v_mul_f32_e32 v44, s4, v44
	v_mul_f32_e32 v45, s4, v45
	v_mul_f32_e32 v46, s4, v46
	v_mul_f32_e32 v47, s4, v47
	v_mul_f32_e32 v44, v4, v44
	v_mul_f32_e32 v45, v5, v45
	v_mul_f32_e32 v46, v6, v46
	v_mul_f32_e32 v47, v7, v47
	global_store_dwordx4 v8, v[44:47], s[0:1] nt
	s_add_u32 s0, s0, 0x1000
	s_addc_u32 s1, s1, 0
	v_xor_b32_e32 v48, 0x80, v3
	ds_read_b64 v[16:17], v48 offset:4096
	v_xor_b32_e32 v49, 0x90, v3
	ds_read_b64 v[18:19], v49 offset:4608
	v_xor_b32_e32 v50, 0xa0, v3
	ds_read_b64 v[20:21], v50 offset:5120
	v_xor_b32_e32 v51, 0xb0, v3
	ds_read_b64 v[22:23], v51 offset:5632
	v_xor_b32_e32 v52, 0xc0, v3
	ds_read_b64 v[24:25], v52 offset:6144
	v_xor_b32_e32 v53, 0xd0, v3
	ds_read_b64 v[26:27], v53 offset:6656
	v_xor_b32_e32 v54, 0xe0, v3
	ds_read_b64 v[28:29], v54 offset:7168
	v_xor_b32_e32 v55, 0xf0, v3
	ds_read_b64 v[30:31], v55 offset:7680
	s_waitcnt lgkmcnt(0)
	v_readlane_b32 s4, v15, 8
	v_lshlrev_b32_e32 v32, 16, v16
	v_and_b32_e32 v33, 0xffff0000, v16
	v_lshlrev_b32_e32 v34, 16, v17
	v_and_b32_e32 v35, 0xffff0000, v17
	v_mul_f32_e32 v32, s4, v32
	v_mul_f32_e32 v33, s4, v33
	v_mul_f32_e32 v34, s4, v34
	v_mul_f32_e32 v35, s4, v35
	v_mul_f32_e32 v32, v4, v32
	v_mul_f32_e32 v33, v5, v33
	v_mul_f32_e32 v34, v6, v34
	v_mul_f32_e32 v35, v7, v35
	global_store_dwordx4 v8, v[32:35], s[0:1] nt
	s_add_u32 s0, s0, 0x1000
	s_addc_u32 s1, s1, 0
	v_readlane_b32 s4, v15, 9
	v_lshlrev_b32_e32 v36, 16, v18
	v_and_b32_e32 v37, 0xffff0000, v18
	v_lshlrev_b32_e32 v38, 16, v19
	v_and_b32_e32 v39, 0xffff0000, v19
	v_mul_f32_e32 v36, s4, v36
	v_mul_f32_e32 v37, s4, v37
	v_mul_f32_e32 v38, s4, v38
	v_mul_f32_e32 v39, s4, v39
	v_mul_f32_e32 v36, v4, v36
	v_mul_f32_e32 v37, v5, v37
	v_mul_f32_e32 v38, v6, v38
	v_mul_f32_e32 v39, v7, v39
	global_store_dwordx4 v8, v[36:39], s[0:1] nt
	s_add_u32 s0, s0, 0x1000
	s_addc_u32 s1, s1, 0
	v_readlane_b32 s4, v15, 10
	v_lshlrev_b32_e32 v40, 16, v20
	v_and_b32_e32 v41, 0xffff0000, v20
	v_lshlrev_b32_e32 v42, 16, v21
	v_and_b32_e32 v43, 0xffff0000, v21
	v_mul_f32_e32 v40, s4, v40
	v_mul_f32_e32 v41, s4, v41
	v_mul_f32_e32 v42, s4, v42
	v_mul_f32_e32 v43, s4, v43
	v_mul_f32_e32 v40, v4, v40
	v_mul_f32_e32 v41, v5, v41
	v_mul_f32_e32 v42, v6, v42
	v_mul_f32_e32 v43, v7, v43
	global_store_dwordx4 v8, v[40:43], s[0:1] nt
	s_add_u32 s0, s0, 0x1000
	s_addc_u32 s1, s1, 0
	v_readlane_b32 s4, v15, 11
	v_lshlrev_b32_e32 v44, 16, v22
	v_and_b32_e32 v45, 0xffff0000, v22
	v_lshlrev_b32_e32 v46, 16, v23
	v_and_b32_e32 v47, 0xffff0000, v23
	v_mul_f32_e32 v44, s4, v44
	v_mul_f32_e32 v45, s4, v45
	v_mul_f32_e32 v46, s4, v46
	v_mul_f32_e32 v47, s4, v47
	v_mul_f32_e32 v44, v4, v44
	v_mul_f32_e32 v45, v5, v45
	v_mul_f32_e32 v46, v6, v46
	v_mul_f32_e32 v47, v7, v47
	global_store_dwordx4 v8, v[44:47], s[0:1] nt
	s_add_u32 s0, s0, 0x1000
	s_addc_u32 s1, s1, 0
	v_readlane_b32 s4, v15, 12
	v_lshlrev_b32_e32 v32, 16, v24
	v_and_b32_e32 v33, 0xffff0000, v24
	v_lshlrev_b32_e32 v34, 16, v25
	v_and_b32_e32 v35, 0xffff0000, v25
	v_mul_f32_e32 v32, s4, v32
	v_mul_f32_e32 v33, s4, v33
	v_mul_f32_e32 v34, s4, v34
	v_mul_f32_e32 v35, s4, v35
	v_mul_f32_e32 v32, v4, v32
	v_mul_f32_e32 v33, v5, v33
	v_mul_f32_e32 v34, v6, v34
	v_mul_f32_e32 v35, v7, v35
	global_store_dwordx4 v8, v[32:35], s[0:1] nt
	s_add_u32 s0, s0, 0x1000
	s_addc_u32 s1, s1, 0
	v_readlane_b32 s4, v15, 13
	v_lshlrev_b32_e32 v36, 16, v26
	v_and_b32_e32 v37, 0xffff0000, v26
	v_lshlrev_b32_e32 v38, 16, v27
	v_and_b32_e32 v39, 0xffff0000, v27
	v_mul_f32_e32 v36, s4, v36
	v_mul_f32_e32 v37, s4, v37
	v_mul_f32_e32 v38, s4, v38
	v_mul_f32_e32 v39, s4, v39
	v_mul_f32_e32 v36, v4, v36
	v_mul_f32_e32 v37, v5, v37
	v_mul_f32_e32 v38, v6, v38
	v_mul_f32_e32 v39, v7, v39
	global_store_dwordx4 v8, v[36:39], s[0:1] nt
	s_add_u32 s0, s0, 0x1000
	s_addc_u32 s1, s1, 0
	v_readlane_b32 s4, v15, 14
	v_lshlrev_b32_e32 v40, 16, v28
	v_and_b32_e32 v41, 0xffff0000, v28
	v_lshlrev_b32_e32 v42, 16, v29
	v_and_b32_e32 v43, 0xffff0000, v29
	v_mul_f32_e32 v40, s4, v40
	v_mul_f32_e32 v41, s4, v41
	v_mul_f32_e32 v42, s4, v42
	v_mul_f32_e32 v43, s4, v43
	v_mul_f32_e32 v40, v4, v40
	v_mul_f32_e32 v41, v5, v41
	v_mul_f32_e32 v42, v6, v42
	v_mul_f32_e32 v43, v7, v43
	global_store_dwordx4 v8, v[40:43], s[0:1] nt
	s_add_u32 s0, s0, 0x1000
	s_addc_u32 s1, s1, 0
	v_readlane_b32 s4, v15, 15
	v_lshlrev_b32_e32 v44, 16, v30
	v_and_b32_e32 v45, 0xffff0000, v30
	v_lshlrev_b32_e32 v46, 16, v31
	v_and_b32_e32 v47, 0xffff0000, v31
	v_mul_f32_e32 v44, s4, v44
	v_mul_f32_e32 v45, s4, v45
	v_mul_f32_e32 v46, s4, v46
	v_mul_f32_e32 v47, s4, v47
	v_mul_f32_e32 v44, v4, v44
	v_mul_f32_e32 v45, v5, v45
	v_mul_f32_e32 v46, v6, v46
	v_mul_f32_e32 v47, v7, v47
	global_store_dwordx4 v8, v[44:47], s[0:1] nt
	s_add_u32 s0, s0, 0x1000
	s_addc_u32 s1, s1, 0
	v_xor_b32_e32 v48, 0x100, v3
	ds_read_b64 v[16:17], v48 offset:8192
	v_xor_b32_e32 v49, 0x110, v3
	ds_read_b64 v[18:19], v49 offset:8704
	v_xor_b32_e32 v50, 0x120, v3
	ds_read_b64 v[20:21], v50 offset:9216
	v_xor_b32_e32 v51, 0x130, v3
	ds_read_b64 v[22:23], v51 offset:9728
	v_xor_b32_e32 v52, 0x140, v3
	ds_read_b64 v[24:25], v52 offset:10240
	v_xor_b32_e32 v53, 0x150, v3
	ds_read_b64 v[26:27], v53 offset:10752
	v_xor_b32_e32 v54, 0x160, v3
	ds_read_b64 v[28:29], v54 offset:11264
	v_xor_b32_e32 v55, 0x170, v3
	ds_read_b64 v[30:31], v55 offset:11776
	s_waitcnt lgkmcnt(0)
	v_readlane_b32 s4, v15, 16
	v_lshlrev_b32_e32 v32, 16, v16
	v_and_b32_e32 v33, 0xffff0000, v16
	v_lshlrev_b32_e32 v34, 16, v17
	v_and_b32_e32 v35, 0xffff0000, v17
	v_mul_f32_e32 v32, s4, v32
	v_mul_f32_e32 v33, s4, v33
	v_mul_f32_e32 v34, s4, v34
	v_mul_f32_e32 v35, s4, v35
	v_mul_f32_e32 v32, v4, v32
	v_mul_f32_e32 v33, v5, v33
	v_mul_f32_e32 v34, v6, v34
	v_mul_f32_e32 v35, v7, v35
	global_store_dwordx4 v8, v[32:35], s[0:1] nt
	s_add_u32 s0, s0, 0x1000
	s_addc_u32 s1, s1, 0
	v_readlane_b32 s4, v15, 17
	v_lshlrev_b32_e32 v36, 16, v18
	v_and_b32_e32 v37, 0xffff0000, v18
	v_lshlrev_b32_e32 v38, 16, v19
	v_and_b32_e32 v39, 0xffff0000, v19
	v_mul_f32_e32 v36, s4, v36
	v_mul_f32_e32 v37, s4, v37
	v_mul_f32_e32 v38, s4, v38
	v_mul_f32_e32 v39, s4, v39
	v_mul_f32_e32 v36, v4, v36
	v_mul_f32_e32 v37, v5, v37
	v_mul_f32_e32 v38, v6, v38
	v_mul_f32_e32 v39, v7, v39
	global_store_dwordx4 v8, v[36:39], s[0:1] nt
	s_add_u32 s0, s0, 0x1000
	s_addc_u32 s1, s1, 0
	v_readlane_b32 s4, v15, 18
	v_lshlrev_b32_e32 v40, 16, v20
	v_and_b32_e32 v41, 0xffff0000, v20
	v_lshlrev_b32_e32 v42, 16, v21
	v_and_b32_e32 v43, 0xffff0000, v21
	v_mul_f32_e32 v40, s4, v40
	v_mul_f32_e32 v41, s4, v41
	v_mul_f32_e32 v42, s4, v42
	v_mul_f32_e32 v43, s4, v43
	v_mul_f32_e32 v40, v4, v40
	v_mul_f32_e32 v41, v5, v41
	v_mul_f32_e32 v42, v6, v42
	v_mul_f32_e32 v43, v7, v43
	global_store_dwordx4 v8, v[40:43], s[0:1] nt
	s_add_u32 s0, s0, 0x1000
	s_addc_u32 s1, s1, 0
	v_readlane_b32 s4, v15, 19
	v_lshlrev_b32_e32 v44, 16, v22
	v_and_b32_e32 v45, 0xffff0000, v22
	v_lshlrev_b32_e32 v46, 16, v23
	v_and_b32_e32 v47, 0xffff0000, v23
	v_mul_f32_e32 v44, s4, v44
	v_mul_f32_e32 v45, s4, v45
	v_mul_f32_e32 v46, s4, v46
	v_mul_f32_e32 v47, s4, v47
	v_mul_f32_e32 v44, v4, v44
	v_mul_f32_e32 v45, v5, v45
	v_mul_f32_e32 v46, v6, v46
	v_mul_f32_e32 v47, v7, v47
	global_store_dwordx4 v8, v[44:47], s[0:1] nt
	s_add_u32 s0, s0, 0x1000
	s_addc_u32 s1, s1, 0
	v_readlane_b32 s4, v15, 20
	v_lshlrev_b32_e32 v32, 16, v24
	v_and_b32_e32 v33, 0xffff0000, v24
	v_lshlrev_b32_e32 v34, 16, v25
	v_and_b32_e32 v35, 0xffff0000, v25
	v_mul_f32_e32 v32, s4, v32
	v_mul_f32_e32 v33, s4, v33
	v_mul_f32_e32 v34, s4, v34
	v_mul_f32_e32 v35, s4, v35
	v_mul_f32_e32 v32, v4, v32
	v_mul_f32_e32 v33, v5, v33
	v_mul_f32_e32 v34, v6, v34
	v_mul_f32_e32 v35, v7, v35
	global_store_dwordx4 v8, v[32:35], s[0:1] nt
	s_add_u32 s0, s0, 0x1000
	s_addc_u32 s1, s1, 0
	v_readlane_b32 s4, v15, 21
	v_lshlrev_b32_e32 v36, 16, v26
	v_and_b32_e32 v37, 0xffff0000, v26
	v_lshlrev_b32_e32 v38, 16, v27
	v_and_b32_e32 v39, 0xffff0000, v27
	v_mul_f32_e32 v36, s4, v36
	v_mul_f32_e32 v37, s4, v37
	v_mul_f32_e32 v38, s4, v38
	v_mul_f32_e32 v39, s4, v39
	v_mul_f32_e32 v36, v4, v36
	v_mul_f32_e32 v37, v5, v37
	v_mul_f32_e32 v38, v6, v38
	v_mul_f32_e32 v39, v7, v39
	global_store_dwordx4 v8, v[36:39], s[0:1] nt
	s_add_u32 s0, s0, 0x1000
	s_addc_u32 s1, s1, 0
	v_readlane_b32 s4, v15, 22
	v_lshlrev_b32_e32 v40, 16, v28
	v_and_b32_e32 v41, 0xffff0000, v28
	v_lshlrev_b32_e32 v42, 16, v29
	v_and_b32_e32 v43, 0xffff0000, v29
	v_mul_f32_e32 v40, s4, v40
	v_mul_f32_e32 v41, s4, v41
	v_mul_f32_e32 v42, s4, v42
	v_mul_f32_e32 v43, s4, v43
	v_mul_f32_e32 v40, v4, v40
	v_mul_f32_e32 v41, v5, v41
	v_mul_f32_e32 v42, v6, v42
	v_mul_f32_e32 v43, v7, v43
	global_store_dwordx4 v8, v[40:43], s[0:1] nt
	s_add_u32 s0, s0, 0x1000
	s_addc_u32 s1, s1, 0
	v_readlane_b32 s4, v15, 23
	v_lshlrev_b32_e32 v44, 16, v30
	v_and_b32_e32 v45, 0xffff0000, v30
	v_lshlrev_b32_e32 v46, 16, v31
	v_and_b32_e32 v47, 0xffff0000, v31
	v_mul_f32_e32 v44, s4, v44
	v_mul_f32_e32 v45, s4, v45
	v_mul_f32_e32 v46, s4, v46
	v_mul_f32_e32 v47, s4, v47
	v_mul_f32_e32 v44, v4, v44
	v_mul_f32_e32 v45, v5, v45
	v_mul_f32_e32 v46, v6, v46
	v_mul_f32_e32 v47, v7, v47
	global_store_dwordx4 v8, v[44:47], s[0:1] nt
	s_add_u32 s0, s0, 0x1000
	s_addc_u32 s1, s1, 0
	v_xor_b32_e32 v48, 0x180, v3
	ds_read_b64 v[16:17], v48 offset:12288
	v_xor_b32_e32 v49, 0x190, v3
	ds_read_b64 v[18:19], v49 offset:12800
	v_xor_b32_e32 v50, 0x1a0, v3
	ds_read_b64 v[20:21], v50 offset:13312
	v_xor_b32_e32 v51, 0x1b0, v3
	ds_read_b64 v[22:23], v51 offset:13824
	v_xor_b32_e32 v52, 0x1c0, v3
	ds_read_b64 v[24:25], v52 offset:14336
	v_xor_b32_e32 v53, 0x1d0, v3
	ds_read_b64 v[26:27], v53 offset:14848
	v_xor_b32_e32 v54, 0x1e0, v3
	ds_read_b64 v[28:29], v54 offset:15360
	v_xor_b32_e32 v55, 0x1f0, v3
	ds_read_b64 v[30:31], v55 offset:15872
	s_waitcnt lgkmcnt(0)
	v_readlane_b32 s4, v15, 24
	v_lshlrev_b32_e32 v32, 16, v16
	v_and_b32_e32 v33, 0xffff0000, v16
	v_lshlrev_b32_e32 v34, 16, v17
	v_and_b32_e32 v35, 0xffff0000, v17
	v_mul_f32_e32 v32, s4, v32
	v_mul_f32_e32 v33, s4, v33
	v_mul_f32_e32 v34, s4, v34
	v_mul_f32_e32 v35, s4, v35
	v_mul_f32_e32 v32, v4, v32
	v_mul_f32_e32 v33, v5, v33
	v_mul_f32_e32 v34, v6, v34
	v_mul_f32_e32 v35, v7, v35
	global_store_dwordx4 v8, v[32:35], s[0:1] nt
	s_add_u32 s0, s0, 0x1000
	s_addc_u32 s1, s1, 0
	v_readlane_b32 s4, v15, 25
	v_lshlrev_b32_e32 v36, 16, v18
	v_and_b32_e32 v37, 0xffff0000, v18
	v_lshlrev_b32_e32 v38, 16, v19
	v_and_b32_e32 v39, 0xffff0000, v19
	v_mul_f32_e32 v36, s4, v36
	v_mul_f32_e32 v37, s4, v37
	v_mul_f32_e32 v38, s4, v38
	v_mul_f32_e32 v39, s4, v39
	v_mul_f32_e32 v36, v4, v36
	v_mul_f32_e32 v37, v5, v37
	v_mul_f32_e32 v38, v6, v38
	v_mul_f32_e32 v39, v7, v39
	global_store_dwordx4 v8, v[36:39], s[0:1] nt
	s_add_u32 s0, s0, 0x1000
	s_addc_u32 s1, s1, 0
	v_readlane_b32 s4, v15, 26
	v_lshlrev_b32_e32 v40, 16, v20
	v_and_b32_e32 v41, 0xffff0000, v20
	v_lshlrev_b32_e32 v42, 16, v21
	v_and_b32_e32 v43, 0xffff0000, v21
	v_mul_f32_e32 v40, s4, v40
	v_mul_f32_e32 v41, s4, v41
	v_mul_f32_e32 v42, s4, v42
	v_mul_f32_e32 v43, s4, v43
	v_mul_f32_e32 v40, v4, v40
	v_mul_f32_e32 v41, v5, v41
	v_mul_f32_e32 v42, v6, v42
	v_mul_f32_e32 v43, v7, v43
	global_store_dwordx4 v8, v[40:43], s[0:1] nt
	s_add_u32 s0, s0, 0x1000
	s_addc_u32 s1, s1, 0
	v_readlane_b32 s4, v15, 27
	v_lshlrev_b32_e32 v44, 16, v22
	v_and_b32_e32 v45, 0xffff0000, v22
	v_lshlrev_b32_e32 v46, 16, v23
	v_and_b32_e32 v47, 0xffff0000, v23
	v_mul_f32_e32 v44, s4, v44
	v_mul_f32_e32 v45, s4, v45
	v_mul_f32_e32 v46, s4, v46
	v_mul_f32_e32 v47, s4, v47
	v_mul_f32_e32 v44, v4, v44
	v_mul_f32_e32 v45, v5, v45
	v_mul_f32_e32 v46, v6, v46
	v_mul_f32_e32 v47, v7, v47
	global_store_dwordx4 v8, v[44:47], s[0:1] nt
	s_add_u32 s0, s0, 0x1000
	s_addc_u32 s1, s1, 0
	v_readlane_b32 s4, v15, 28
	v_lshlrev_b32_e32 v32, 16, v24
	v_and_b32_e32 v33, 0xffff0000, v24
	v_lshlrev_b32_e32 v34, 16, v25
	v_and_b32_e32 v35, 0xffff0000, v25
	v_mul_f32_e32 v32, s4, v32
	v_mul_f32_e32 v33, s4, v33
	v_mul_f32_e32 v34, s4, v34
	v_mul_f32_e32 v35, s4, v35
	v_mul_f32_e32 v32, v4, v32
	v_mul_f32_e32 v33, v5, v33
	v_mul_f32_e32 v34, v6, v34
	v_mul_f32_e32 v35, v7, v35
	global_store_dwordx4 v8, v[32:35], s[0:1] nt
	s_add_u32 s0, s0, 0x1000
	s_addc_u32 s1, s1, 0
	v_readlane_b32 s4, v15, 29
	v_lshlrev_b32_e32 v36, 16, v26
	v_and_b32_e32 v37, 0xffff0000, v26
	v_lshlrev_b32_e32 v38, 16, v27
	v_and_b32_e32 v39, 0xffff0000, v27
	v_mul_f32_e32 v36, s4, v36
	v_mul_f32_e32 v37, s4, v37
	v_mul_f32_e32 v38, s4, v38
	v_mul_f32_e32 v39, s4, v39
	v_mul_f32_e32 v36, v4, v36
	v_mul_f32_e32 v37, v5, v37
	v_mul_f32_e32 v38, v6, v38
	v_mul_f32_e32 v39, v7, v39
	global_store_dwordx4 v8, v[36:39], s[0:1] nt
	s_add_u32 s0, s0, 0x1000
	s_addc_u32 s1, s1, 0
	v_readlane_b32 s4, v15, 30
	v_lshlrev_b32_e32 v40, 16, v28
	v_and_b32_e32 v41, 0xffff0000, v28
	v_lshlrev_b32_e32 v42, 16, v29
	v_and_b32_e32 v43, 0xffff0000, v29
	v_mul_f32_e32 v40, s4, v40
	v_mul_f32_e32 v41, s4, v41
	v_mul_f32_e32 v42, s4, v42
	v_mul_f32_e32 v43, s4, v43
	v_mul_f32_e32 v40, v4, v40
	v_mul_f32_e32 v41, v5, v41
	v_mul_f32_e32 v42, v6, v42
	v_mul_f32_e32 v43, v7, v43
	global_store_dwordx4 v8, v[40:43], s[0:1] nt
	s_add_u32 s0, s0, 0x1000
	s_addc_u32 s1, s1, 0
	v_readlane_b32 s4, v15, 31
	v_lshlrev_b32_e32 v44, 16, v30
	v_and_b32_e32 v45, 0xffff0000, v30
	v_lshlrev_b32_e32 v46, 16, v31
	v_and_b32_e32 v47, 0xffff0000, v31
	v_mul_f32_e32 v44, s4, v44
	v_mul_f32_e32 v45, s4, v45
	v_mul_f32_e32 v46, s4, v46
	v_mul_f32_e32 v47, s4, v47
	v_mul_f32_e32 v44, v4, v44
	v_mul_f32_e32 v45, v5, v45
	v_mul_f32_e32 v46, v6, v46
	v_mul_f32_e32 v47, v7, v47
	global_store_dwordx4 v8, v[44:47], s[0:1] nt
	s_add_u32 s0, s0, 0x1000
	s_addc_u32 s1, s1, 0
	s_waitcnt lgkmcnt(0)

.LBB0_1262:
	v_readlane_b32 s2, v248, 0
	v_readlane_b32 s3, v248, 1
	s_cmp_lt_i32 s2, 12
	s_cselect_b64 s[2:3], -1, 0
	s_and_b64 s[0:1], s[2:3], s[0:1]
	s_andn2_b64 vcc, exec, s[0:1]
	s_cbranch_vccnz .LBB0_1270
	v_lshl_or_b32 v16, s82, 3, v210
	v_add_u32_e32 v16, 0x4000, v16
	s_movk_i32 s0, 0x4080
	v_cmp_gt_i32_e32 vcc, s0, v16
	s_and_saveexec_b64 s[0:1], vcc
	s_cbranch_execz .LBB0_1270
	v_lshlrev_b32_e32 v0, 2, v0
	v_and_b32_e32 v17, 0xfc, v0
	v_lshlrev_b32_e32 v18, 2, v17
	global_load_dwordx4 v[0:3], v18, s[90:91]
	global_load_dwordx4 v[4:7], v18, s[90:91] offset:1024
	global_load_dwordx4 v[8:11], v18, s[90:91] offset:2048
	global_load_dwordx4 v[12:15], v18, s[90:91] offset:3072
	v_lshlrev_b32_e32 v22, 1, v17
	v_mbcnt_lo_u32_b32 v17, -1, 0
	v_mbcnt_hi_u32_b32 v17, -1, v17
	v_and_b32_e32 v25, 64, v17
	v_xor_b32_e32 v24, 1, v17
	v_add_u32_e32 v25, 64, v25
	v_cmp_lt_i32_e32 vcc, v24, v25
	v_mov_b32_e32 v19, 0
	v_lshl_add_u64 v[20:21], s[94:95], 0, v[18:19]
	v_cndmask_b32_e32 v24, v17, v24, vcc
	v_lshlrev_b32_e32 v44, 2, v24
	v_xor_b32_e32 v24, 2, v17
	v_cmp_lt_i32_e32 vcc, v24, v25
	s_mov_b64 s[0:1], 0xb3d6400
	v_mov_b32_e32 v23, v19
	v_cndmask_b32_e32 v24, v17, v24, vcc
	v_lshlrev_b32_e32 v45, 2, v24
	v_xor_b32_e32 v24, 4, v17
	v_cmp_lt_i32_e32 vcc, v24, v25
	v_lshl_add_u64 v[20:21], v[20:21], 0, s[0:1]
	v_lshl_add_u64 v[22:23], s[94:95], 0, v[22:23]
	v_cndmask_b32_e32 v24, v17, v24, vcc
	v_lshlrev_b32_e32 v46, 2, v24
	v_xor_b32_e32 v24, 8, v17
	v_cmp_lt_i32_e32 vcc, v24, v25
	s_mov_b64 s[0:1], 0x1f80000
	v_lshl_add_u64 v[22:23], v[22:23], 0, s[0:1]
	v_cndmask_b32_e32 v24, v17, v24, vcc
	v_lshlrev_b32_e32 v47, 2, v24
	v_xor_b32_e32 v24, 16, v17
	v_cmp_lt_i32_e32 vcc, v24, v25
	s_waitcnt lgkmcnt(0)
	s_lshl_b32 s4, s96, 3
	s_mov_b64 s[0:1], 0
	v_cndmask_b32_e32 v24, v17, v24, vcc
	v_lshlrev_b32_e32 v48, 2, v24
	v_xor_b32_e32 v24, 32, v17
	v_cmp_lt_i32_e32 vcc, v24, v25
	s_movk_i32 s5, 0x3fff
	v_mov_b32_e32 v50, 0x3727c5ac
	v_cndmask_b32_e32 v17, v17, v24, vcc
	v_lshlrev_b32_e32 v49, 2, v17
	v_lshl_add_u64 v[24:25], s[92:93], 0, v[18:19]
	s_mov_b32 s6, 0x800000
	s_movk_i32 s7, 0x407f
	s_branch .LBB0_1266
